# adds: new-max tail (alpha exp, -m update) executed only on the rare re-max path
# speedup vs baseline: 1.0182x; 1.0038x over previous
; DI void diff_unit(KP p, int l, int b, int h, int qb, int isctx, float lamv, float lam_init, char* ldsc) {
;     ...
;     if (need) {
; #pragma unroll
;       for (int d = 0; d < 4; ++d) o[d] *= alpha;
;     }
.LBB0_475:
	s_andn2_b64 vcc, exec, s[4:5]
	s_cbranch_vccnz .LBB0_477
	v_pk_mul_f32 v[64:65], v[64:65], v[140:141] op_sel_hi:[1,0]
	v_pk_mul_f32 v[62:63], v[62:63], v[140:141] op_sel_hi:[1,0]
	v_pk_mul_f32 v[60:61], v[60:61], v[140:141] op_sel_hi:[1,0]
	v_pk_mul_f32 v[58:59], v[58:59], v[140:141] op_sel_hi:[1,0]
	v_pk_mul_f32 v[56:57], v[56:57], v[140:141] op_sel_hi:[1,0]
	v_pk_mul_f32 v[54:55], v[54:55], v[140:141] op_sel_hi:[1,0]
	v_pk_mul_f32 v[52:53], v[52:53], v[140:141] op_sel_hi:[1,0]
	v_pk_mul_f32 v[50:51], v[50:51], v[140:141] op_sel_hi:[1,0]
	v_pk_mul_f32 v[48:49], v[48:49], v[140:141] op_sel_hi:[1,0]
	v_pk_mul_f32 v[46:47], v[46:47], v[140:141] op_sel_hi:[1,0]
	v_pk_mul_f32 v[44:45], v[44:45], v[140:141] op_sel_hi:[1,0]
	v_pk_mul_f32 v[42:43], v[42:43], v[140:141] op_sel_hi:[1,0]
	v_pk_mul_f32 v[40:41], v[40:41], v[140:141] op_sel_hi:[1,0]
	v_pk_mul_f32 v[38:39], v[38:39], v[140:141] op_sel_hi:[1,0]
	v_pk_mul_f32 v[36:37], v[36:37], v[140:141] op_sel_hi:[1,0]
	v_pk_mul_f32 v[34:35], v[34:35], v[140:141] op_sel_hi:[1,0]
	v_pk_mul_f32 v[32:33], v[32:33], v[140:141] op_sel_hi:[1,0]
	v_pk_mul_f32 v[30:31], v[30:31], v[140:141] op_sel_hi:[1,0]
	v_pk_mul_f32 v[28:29], v[28:29], v[140:141] op_sel_hi:[1,0]
	v_pk_mul_f32 v[26:27], v[26:27], v[140:141] op_sel_hi:[1,0]
	v_pk_mul_f32 v[24:25], v[24:25], v[140:141] op_sel_hi:[1,0]
	v_pk_mul_f32 v[22:23], v[22:23], v[140:141] op_sel_hi:[1,0]
	v_pk_mul_f32 v[20:21], v[20:21], v[140:141] op_sel_hi:[1,0]
	v_pk_mul_f32 v[18:19], v[18:19], v[140:141] op_sel_hi:[1,0]
	v_pk_mul_f32 v[16:17], v[16:17], v[140:141] op_sel_hi:[1,0]
	v_pk_mul_f32 v[14:15], v[14:15], v[140:141] op_sel_hi:[1,0]
	v_pk_mul_f32 v[12:13], v[12:13], v[140:141] op_sel_hi:[1,0]
	v_pk_mul_f32 v[10:11], v[10:11], v[140:141] op_sel_hi:[1,0]
	v_pk_mul_f32 v[8:9], v[8:9], v[140:141] op_sel_hi:[1,0]
	v_pk_mul_f32 v[6:7], v[6:7], v[140:141] op_sel_hi:[1,0]
	v_pk_mul_f32 v[4:5], v[4:5], v[140:141] op_sel_hi:[1,0]
	v_pk_mul_f32 v[2:3], v[2:3], v[140:141] op_sel_hi:[1,0]
	v_mov_b32_e32 v140, 1.0
; #define MFMA32(a, b, c) __builtin_amdgcn_mfma_f32_32x32x16_bf16((a), (b), (c), 0, 0, 0)
; #define VLOAD(dst, sbv, q) do { _Pragma("unroll") for (int d_ = 0; d_ < 4; ++d_) dst[d_] = *(const lds_bf16x8*)((sbv) + vo[q] + d_ * 4096); } while (0)
; #define FENCE __builtin_amdgcn_sched_barrier(0)
; DI void diff_unit(KP p, int l, int b, int h, int qb, int isctx, float lamv, float lam_init, char* ldsc) {
;     ...
;     const lds_u8* sbv = L + stg * STG + 16384;
;     const lds_u8* sbk = L + stg1 * STG + comp * 8192;
;     bf16x8 kf[2][4];
;     f32x16 st[2];
; #pragma unroll
;     for (int t = 0; t < 2; ++t)
; #pragma unroll
;       for (int ks = 0; ks < 4; ++ks) kf[t][ks] = *(const lds_bf16x8*)(sbk + ko[ks] + t * 4096);
;     FENCE;
;     pv_grp(o, vA, P[0]); pv_grp(o, vB, P[1]);
;     VLOAD(vA, sbv, 2); VLOAD(vB, sbv, 3);
;     FENCE;
; #pragma unroll
;     for (int i = 0; i < 16; ++i) { st[0][i] = 0.f; st[1][i] = 0.f; }
; #pragma unroll
;     for (int ks = 0; ks < 4; ++ks) st[0] = MFMA32(kf[0][ks], qf[ks], st[0]);
; #pragma unroll
;     for (int ks = 0; ks < 4; ++ks) st[1] = MFMA32(kf[1][ks], qf[ks], st[1]);
;     FENCE;
;     pv_grp(o, vA, P[2]);
;     const float mx = tile_max(st);
;     need = !__all(mx <= m + 8.0f);
;     const float mn = need ? fmaxf(m, mx) : m;
;     alpha = __builtin_amdgcn_exp2f(m - mn);
;     FENCE;
.LBB0_477:
	s_add_i32 s2, s17, 1
	s_and_b32 s16, s2, 3
	s_lshl_b32 s2, s16, 15
	s_add_i32 s15, s2, 0
	s_add_i32 s2, s15, s14
	v_add_u32_e32 v0, s2, v141
	v_add_u32_e32 v251, s2, v145
	v_add_u32_e32 v191, s2, v147
	v_add_u32_e32 v216, s2, v148
	ds_read_b128 v[154:157], v0
	ds_read_b128 v[192:195], v0 offset:4096
	ds_read_b128 v[196:199], v251
	ds_read_b128 v[200:203], v251 offset:4096
	ds_read_b128 v[204:207], v191
	ds_read_b128 v[208:211], v191 offset:4096
	ds_read_b128 v[212:215], v216
	ds_read_b128 v[216:219], v216 offset:4096
	s_lshl_b32 s2, s17, 15
	s_add_i32 s2, s2, 0
	s_waitcnt lgkmcnt(8)
	v_mfma_f32_32x32x16_bf16 v[50:65], v[86:89], v[66:69], v[50:65]
	v_add_u32_e32 v0, s2, v149
	ds_read_b128 v[220:223], v0 offset:24576
	ds_read_b128 v[224:227], v0 offset:28672
	s_add_i32 s18, s3, 0xc0
	s_add_i32 s19, s10, 64
	s_cmp_eq_u32 s11, 0
	s_cselect_b32 s19, s18, s19
	s_add_i32 s18, s17, 3
	s_and_b32 s18, s18, 3
	s_lshl_b32 s18, s18, 15
	s_add_i32 s18, s13, s18
	v_mad_i64_i32 v[244:245], vcc, s19, v185, v[136:137]
	v_lshl_add_u64 v[246:247], v[244:245], 0, s[96:97]
	v_lshl_add_u64 v[244:245], v[244:245], 0, s[52:53]
	v_lshl_add_u64 v[248:249], v[138:139], 0, s[60:61]
	s_mov_b32 m0, s18
	v_mfma_f32_32x32x16_bf16 v[34:49], v[82:85], v[66:69], v[34:49]
	global_load_lds_dwordx4 v[246:247], off
	s_add_i32 m0, s18, 0x2000
	v_mfma_f32_32x32x16_bf16 v[18:33], v[78:81], v[66:69], v[18:33]
	v_mfma_f32_32x32x16_bf16 v[2:17], v[74:77], v[66:69], v[2:17]
	v_mov_b64_e32 v[66:67], v[252:253]
	v_mov_b64_e32 v[68:69], v[252:253]
	v_mov_b64_e32 v[74:75], v[252:253]
	global_load_lds_dwordx4 v[244:245], off
	s_add_i32 m0, s18, 0x4000
	v_mfma_f32_32x32x16_bf16 v[50:65], v[126:129], v[70:73], v[50:65]
	v_mov_b64_e32 v[76:77], v[252:253]
	v_mov_b64_e32 v[78:79], v[252:253]
	v_mov_b64_e32 v[80:81], v[252:253]
	ds_read_b128 v[126:129], v0 offset:20480
	v_mfma_f32_32x32x16_bf16 v[34:49], v[122:125], v[70:73], v[34:49]
	v_mov_b64_e32 v[82:83], v[252:253]
	v_mov_b64_e32 v[84:85], v[252:253]
	ds_read_b128 v[122:125], v0 offset:16384
	v_add_u32_e32 v0, s2, v146
	ds_read_b128 v[228:231], v0 offset:16384
	ds_read_b128 v[232:235], v0 offset:20480
	ds_read_b128 v[236:239], v0 offset:24576
	ds_read_b128 v[240:243], v0 offset:28672
	v_mfma_f32_32x32x16_bf16 v[18:33], v[94:97], v[70:73], v[18:33]
	v_mov_b64_e32 v[86:87], v[252:253]
	v_mov_b64_e32 v[88:89], v[252:253]
	v_mov_b64_e32 v[94:95], v[252:253]
	v_mov_b64_e32 v[96:97], v[252:253]
	v_mfma_f32_32x32x16_bf16 v[2:17], v[90:93], v[70:73], v[2:17]
	v_mov_b64_e32 v[70:71], v[252:253]
	v_mov_b64_e32 v[72:73], v[252:253]
	v_mov_b64_e32 v[90:91], v[252:253]
	v_mov_b64_e32 v[92:93], v[252:253]
	global_load_lds_dwordx4 v[248:249], off
	s_add_i32 m0, s18, 0x6000
	s_waitcnt lgkmcnt(8)
	v_mfma_f32_32x32x16_bf16 v[66:81], v[192:195], v[98:101], v[66:81]
	v_mfma_f32_32x32x16_bf16 v[82:97], v[154:157], v[98:101], v[82:97]
	v_mfma_f32_32x32x16_bf16 v[66:81], v[200:203], v[102:105], v[66:81]
	v_mfma_f32_32x32x16_bf16 v[82:97], v[196:199], v[102:105], v[82:97]
	global_load_lds_dwordx4 v[138:139], off
	v_mfma_f32_32x32x16_bf16 v[66:81], v[208:211], v[106:109], v[66:81]
	v_mfma_f32_32x32x16_bf16 v[82:97], v[204:207], v[106:109], v[82:97]
	v_mfma_f32_32x32x16_bf16 v[66:81], v[216:219], v[110:113], v[66:81]
	v_mfma_f32_32x32x16_bf16 v[82:97], v[212:215], v[110:113], v[82:97]
	s_waitcnt lgkmcnt(0)
	v_mfma_f32_32x32x16_bf16 v[50:65], v[122:125], v[118:121], v[50:65]
	s_nop 9
	v_max3_f32 v0, v82, v83, v84
	v_max3_f32 v250, v66, v67, v68
	v_mfma_f32_32x32x16_bf16 v[34:49], v[126:129], v[118:121], v[34:49]
	v_max3_f32 v0, v0, v85, v86
	v_max3_f32 v250, v250, v69, v70
	v_max3_f32 v0, v0, v87, v88
	v_max3_f32 v250, v250, v71, v72
	v_max3_f32 v0, v0, v89, v90
	v_mfma_f32_32x32x16_bf16 v[18:33], v[220:223], v[118:121], v[18:33]
	v_max3_f32 v250, v250, v73, v74
	v_max3_f32 v0, v0, v91, v92
	v_max3_f32 v250, v250, v75, v76
	v_max3_f32 v0, v0, v93, v94
	v_max3_f32 v250, v250, v77, v78
	v_mfma_f32_32x32x16_bf16 v[2:17], v[224:227], v[118:121], v[2:17]
	v_max3_f32 v0, v0, v95, v96
	v_max3_f32 v250, v250, v79, v80
	v_max_f32_e32 v0, v0, v97
	v_max_f32_e32 v250, v250, v81
	v_max_f32_e32 v0, v0, v250
	v_mov_b32_e32 v118, v0
	s_nop 1
	v_permlane32_swap_b32_e32 v0, v118
	v_max_f32_e32 v0, v0, v118
	v_cmp_ge_f32_e32 vcc, 0x41000000, v0
	s_cmp_lg_u64 vcc, exec
	s_cselect_b64 s[4:5], -1, 0
	s_cbranch_scc0 .Ldiff_nosub
	v_max_f32_e32 v0, 0, v0
	v_sub_f32_e32 v252, v252, v0
	v_exp_f32_e64 v140, -v0
	v_mov_b32_e32 v253, v252
	v_sub_f32_e32 v82, v82, v0
	v_sub_f32_e32 v83, v83, v0
	v_sub_f32_e32 v84, v84, v0
	v_sub_f32_e32 v85, v85, v0
	v_sub_f32_e32 v86, v86, v0
	v_sub_f32_e32 v87, v87, v0
	v_sub_f32_e32 v88, v88, v0
	v_sub_f32_e32 v89, v89, v0
	v_sub_f32_e32 v90, v90, v0
	v_sub_f32_e32 v91, v91, v0
	v_sub_f32_e32 v92, v92, v0
	v_sub_f32_e32 v93, v93, v0
	v_sub_f32_e32 v94, v94, v0
	v_sub_f32_e32 v95, v95, v0
	v_sub_f32_e32 v96, v96, v0
	v_sub_f32_e32 v97, v97, v0
	v_sub_f32_e32 v66, v66, v0
	v_sub_f32_e32 v67, v67, v0
	v_sub_f32_e32 v68, v68, v0
	v_sub_f32_e32 v69, v69, v0
	v_sub_f32_e32 v70, v70, v0
	v_sub_f32_e32 v71, v71, v0
	v_sub_f32_e32 v72, v72, v0
	v_sub_f32_e32 v73, v73, v0
	v_sub_f32_e32 v74, v74, v0
	v_sub_f32_e32 v75, v75, v0
	v_sub_f32_e32 v76, v76, v0
	v_sub_f32_e32 v77, v77, v0
	v_sub_f32_e32 v78, v78, v0
	v_sub_f32_e32 v79, v79, v0
	v_sub_f32_e32 v80, v80, v0
	v_sub_f32_e32 v81, v81, v0
